# ffn_in shift-bias tasks moved from the ret phase prologue to the odd (gmlp+pool) workgroups of the mix phase, which had slack
# speedup vs baseline: 1.0160x; 1.0160x over previous
.Lbias_task:
	v_writelane_b32 v255, s40, 42
	v_writelane_b32 v255, s41, 43
	v_writelane_b32 v255, s42, 44
	v_writelane_b32 v255, s43, 45
	v_writelane_b32 v255, s44, 46
	v_writelane_b32 v255, s45, 47
	v_writelane_b32 v255, s46, 48
	v_writelane_b32 v255, s47, 49
	v_writelane_b32 v255, s48, 50
	v_writelane_b32 v255, s49, 51
	v_writelane_b32 v255, s50, 52
	v_writelane_b32 v255, s51, 53
	v_writelane_b32 v255, s52, 54
	v_writelane_b32 v255, s53, 55
	v_writelane_b32 v255, s54, 56
	v_writelane_b32 v255, s55, 57
	s_mov_b64 s[50:51], exec
	v_mul_u32_u24_e32 v0, 0xc0, v228
	ds_write_b128 v0, v[128:131] offset:0
	ds_write_b128 v0, v[132:135] offset:16
	ds_write_b128 v0, v[136:139] offset:32
	ds_write_b128 v0, v[140:143] offset:48
	ds_write_b128 v0, v[144:147] offset:64
	ds_write_b128 v0, v[148:151] offset:80
	ds_write_b128 v0, v[152:155] offset:96
	ds_write_b128 v0, v[156:159] offset:112
	ds_write_b128 v0, v[160:163] offset:128
	ds_write_b128 v0, v[164:167] offset:144
	ds_write_b128 v0, v[168:171] offset:160
	ds_write_b128 v0, v[172:175] offset:176
	s_and_b32 s54, s28, 0xff
	s_bfe_u32 s47, s28, 0x10008
	s_bfe_u32 s48, s28, 0x10009
	s_lshr_b32 s49, s28, 10
	s_movk_i32 s55, 0x58
	s_cmp_eq_u32 s48, 1
	s_cbranch_scc0 .Lbias_nt
	s_movk_i32 s55, 0xb0

.Lbias_col0:
	v_lshlrev_b32_e32 v162, 2, v162
	v_add_u32_e32 v163, s46, v162
	v_add_u32_e32 v164, s46, v163
	v_add_u32_e32 v165, s46, v164
	v_add_u32_e32 v166, s46, v165
	v_and_b32_e32 v160, 15, v160
	v_cmp_eq_u32_e64 s[52:53], 0, v160
	s_nop 4
	s_and_b64 exec, exec, s[52:53]
	global_store_dword v162, v80, s[44:45] sc1
	global_store_dword v162, v88, s[44:45] offset:4 sc1
	global_store_dword v163, v81, s[44:45] sc1
	global_store_dword v163, v89, s[44:45] offset:4 sc1
	global_store_dword v164, v82, s[44:45] sc1
	global_store_dword v164, v90, s[44:45] offset:4 sc1
	global_store_dword v165, v83, s[44:45] sc1
	global_store_dword v165, v91, s[44:45] offset:4 sc1
	global_store_dword v166, v84, s[44:45] sc1
	global_store_dword v166, v92, s[44:45] offset:4 sc1
	s_mov_b64 exec, s[50:51]
	s_add_i32 s54, s54, s70
	s_cmp_lt_i32 s54, s55
	s_cbranch_scc1 .Lbias_again
	v_mul_u32_u24_e32 v0, 0xc0, v228
	ds_read_b128 v[128:131], v0 offset:0
	ds_read_b128 v[132:135], v0 offset:16
	ds_read_b128 v[136:139], v0 offset:32
	ds_read_b128 v[140:143], v0 offset:48
	ds_read_b128 v[144:147], v0 offset:64
	ds_read_b128 v[148:151], v0 offset:80
	ds_read_b128 v[152:155], v0 offset:96
	ds_read_b128 v[156:159], v0 offset:112
	ds_read_b128 v[160:163], v0 offset:128
	ds_read_b128 v[164:167], v0 offset:144
	ds_read_b128 v[168:171], v0 offset:160
	ds_read_b128 v[172:175], v0 offset:176
	s_mov_b32 s28, s49
	v_readlane_b32 s40, v255, 42
	v_readlane_b32 s41, v255, 43
	v_readlane_b32 s42, v255, 44
	v_readlane_b32 s43, v255, 45
	v_readlane_b32 s44, v255, 46
	v_readlane_b32 s45, v255, 47
	v_readlane_b32 s46, v255, 48
	v_readlane_b32 s47, v255, 49
	v_readlane_b32 s48, v255, 50
	v_readlane_b32 s49, v255, 51
	v_readlane_b32 s50, v255, 52
	v_readlane_b32 s51, v255, 53
	v_readlane_b32 s52, v255, 54
	v_readlane_b32 s53, v255, 55
	v_readlane_b32 s54, v255, 56
	v_readlane_b32 s55, v255, 57
	s_waitcnt lgkmcnt(0)
	s_nop 3
	s_cmp_eq_u32 s28, 1
	s_cbranch_scc1 .Lbias_ret1
	s_cmp_eq_u32 s28, 2
	s_cbranch_scc1 .Lbias_ret2
	s_cmp_eq_u32 s28, 0
	s_cbranch_scc1 .Lbias_ret4
	s_branch .Lbias_ret3
.LBB0_286:
.Lbias_ret2:
.LBB0_291:
	s_cmpk_gt_i32 s30, 0xff
	s_cbranch_scc1 .LBB0_385
	v_readlane_b32 s2, v255, 36
	s_lshl_b32 s0, s2, 3
	s_lshl_b32 s46, s90, 2
	s_add_i32 s47, s46, s0
	s_sub_i32 s33, 1, s90
	s_add_i32 s48, s47, -16
	s_cmp_eq_u32 s90, 0
	s_cselect_b64 s[36:37], -1, 0
	s_and_b64 s[0:1], s[36:37], exec
	s_movk_i32 s0, 0x500
	s_mul_i32 s33, s33, 0x12000
	s_cselect_b32 s49, s0, 0x700
	s_add_i32 s50, s69, 0x9000
	s_add_i32 s51, s69, 0x4800
	s_mov_b32 s52, s30
	s_mov_b32 s53, s30
	v_readlane_b32 s3, v255, 37
	s_branch .LBB0_294

.LBB0_394:
	s_and_b32 s28, s33, -2
	s_add_i32 s28, s28, s90
	s_cmpk_gt_i32 s28, 0xaf
	s_cbranch_scc1 .Lbias_ret4
	v_readlane_b32 s2, v255, 36
	s_nop 3
	s_lshl_b32 s2, s2, 8
	s_or_b32 s28, s28, s2
	s_or_b32 s28, s28, 0x200
	s_branch .Lbias_task
